# hand-written WIN Q/K (rope) epilogue case: separate rotating/non-rotating wave paths, hoisted addressing, double-buffered rope table loads, packed math
# speedup vs baseline: 1.0246x; 1.0030x over previous
.LBB0_1055:
	s_andn2_b64 vcc, exec, s[0:1]
	s_cbranch_vccnz .LBB0_1112
	s_lshl_b32 s78, s70, 8
	v_add_u32_e32 v153, s78, v149
	s_lshl_b32 s3, s71, 1
	s_lshr_b32 s37, 0x1000, s3
	s_cmp_eq_u32 s41, 3
	s_mov_b32 s76, 0xa800000
	s_cselect_b32 s76, s76, 0xc000000
	s_cselect_b32 s0, 0x3e38aa3b, 1.0
	v_mov_b32_e32 v150, s0
	s_add_u32 s80, s82, s76
	s_addc_u32 s81, s83, 0
	s_lshl_b32 s77, -1, s3
	s_not_b32 s77, s77
	s_lshl_b32 s76, s71, 2
	s_or_b32 s76, s76, s58
	v_add_u32_e32 v154, s59, v151
	v_ashrrev_i32_e32 v155, 31, v154
	v_lshl_add_u64 v[154:155], v[154:155], 1, s[80:81]
	v_ashrrev_i32_e32 v0, 12, v153
	v_mad_i32_i24 v174, v0, 12, s76
	v_ashrrev_i32_e32 v175, 31, v174
	v_and_b32_e32 v172, s77, v153
	v_mul_u32_u24_e32 v172, s37, v172
	v_and_b32_e32 v173, 0xfff, v153
	v_lshrrev_b32_e32 v173, s3, v173
	v_add_lshl_u32 v0, v172, v173, 7
	v_lshl_add_u64 v[130:131], v[154:155], 0, v[0:1]
	v_lshlrev_b64 v[174:175], 19, v[174:175]
	v_lshl_add_u64 v[130:131], v[130:131], 0, v[174:175]
	s_lshr_b32 s6, 0x800, s3
	s_mov_b32 s7, 0
	s_mul_i32 s0, s6, 5
	s_mov_b32 s1, 0
	s_mov_b32 s80, 0x100000
	s_mov_b32 s81, 0
	s_and_b64 vcc, exec, s[22:23]
	s_cbranch_vccz .Lqk_nonrot
	v_cmp_eq_u32_e32 vcc, 0, v182
	v_cmp_gt_i32_e64 s[76:77], 2, v182
	s_nop 0
	v_cndmask_b32_e64 v0, 1.0, -1.0, vcc
	v_cndmask_b32_e64 v152, 0, v0, s[76:77]
	v_add_u32_e32 v134, s60, v153
	v_ashrrev_i32_e32 v135, 31, v134
	v_lshlrev_b64 v[134:135], 6, v[134:135]
	v_lshl_add_u64 v[134:135], s[20:21], 0, v[134:135]
	v_add_co_u32_e32 v136, vcc, 0x2000, v134
	s_nop 1
	v_addc_co_u32_e32 v137, vcc, 0, v135, vcc
	v_cmp_lt_i32_e32 vcc, v221, v223
	s_nop 1
	v_cndmask_b32_e32 v0, v219, v221, vcc
	v_lshlrev_b32_e32 v0, 2, v0
	global_load_dwordx4 v[154:157], v[134:135], off offset:0
	global_load_dwordx4 v[158:161], v[134:135], off offset:16
	global_load_dwordx4 v[162:165], v[134:135], off offset:32
	global_load_dwordx4 v[166:169], v[134:135], off offset:48
	s_waitcnt vmcnt(0)
	v_cndmask_b32_e64 v154, 1.0, v154, s[76:77]
	v_cndmask_b32_e64 v155, 1.0, v155, s[76:77]
	v_cndmask_b32_e64 v156, 1.0, v156, s[76:77]
	v_cndmask_b32_e64 v157, 1.0, v157, s[76:77]
	v_cndmask_b32_e64 v158, 1.0, v158, s[76:77]
	v_cndmask_b32_e64 v159, 1.0, v159, s[76:77]
	v_cndmask_b32_e64 v160, 1.0, v160, s[76:77]
	v_cndmask_b32_e64 v161, 1.0, v161, s[76:77]
	v_pk_mul_f32 v[162:163], v[152:153], v[162:163] op_sel_hi:[0,1]
	v_pk_mul_f32 v[164:165], v[152:153], v[164:165] op_sel_hi:[0,1]
	v_pk_mul_f32 v[166:167], v[152:153], v[166:167] op_sel_hi:[0,1]
	v_pk_mul_f32 v[168:169], v[152:153], v[168:169] op_sel_hi:[0,1]
	ds_bpermute_b32 v170, v0, v126
	ds_bpermute_b32 v171, v0, v127
	ds_bpermute_b32 v172, v0, v128
	ds_bpermute_b32 v173, v0, v129
	ds_bpermute_b32 v174, v0, v122
	ds_bpermute_b32 v175, v0, v123
	ds_bpermute_b32 v176, v0, v124
	ds_bpermute_b32 v177, v0, v125
	s_waitcnt lgkmcnt(0)
	v_pk_mul_f32 v[170:171], v[162:163], v[170:171]
	v_pk_mul_f32 v[172:173], v[164:165], v[172:173]
	v_pk_mul_f32 v[174:175], v[166:167], v[174:175]
	v_pk_mul_f32 v[176:177], v[168:169], v[176:177]
	v_pk_fma_f32 v[170:171], v[126:127], v[154:155], v[170:171]
	v_pk_fma_f32 v[172:173], v[128:129], v[156:157], v[172:173]
	v_pk_fma_f32 v[174:175], v[122:123], v[158:159], v[174:175]
	v_pk_fma_f32 v[176:177], v[124:125], v[160:161], v[176:177]
	v_pk_mul_f32 v[170:171], v[150:151], v[170:171] op_sel_hi:[0,1]
	v_pk_mul_f32 v[172:173], v[150:151], v[172:173] op_sel_hi:[0,1]
	v_pk_mul_f32 v[174:175], v[150:151], v[174:175] op_sel_hi:[0,1]
	v_pk_mul_f32 v[176:177], v[150:151], v[176:177] op_sel_hi:[0,1]
	v_cvt_pk_bf16_f32 v170, v170, v171
	v_cvt_pk_bf16_f32 v171, v172, v173
	v_cvt_pk_bf16_f32 v172, v174, v175
	v_cvt_pk_bf16_f32 v173, v176, v177
	global_store_dwordx4 v[130:131], v[170:173], off
	v_lshl_add_u64 v[132:133], v[130:131], 0, s[80:81]
	ds_bpermute_b32 v170, v0, v94
	ds_bpermute_b32 v171, v0, v95
	ds_bpermute_b32 v172, v0, v96
	ds_bpermute_b32 v173, v0, v97
	ds_bpermute_b32 v174, v0, v90
	ds_bpermute_b32 v175, v0, v91
	ds_bpermute_b32 v176, v0, v92
	ds_bpermute_b32 v177, v0, v93
	s_waitcnt lgkmcnt(0)
	v_pk_mul_f32 v[170:171], v[162:163], v[170:171]
	v_pk_mul_f32 v[172:173], v[164:165], v[172:173]
	v_pk_mul_f32 v[174:175], v[166:167], v[174:175]
	v_pk_mul_f32 v[176:177], v[168:169], v[176:177]
	v_pk_fma_f32 v[170:171], v[94:95], v[154:155], v[170:171]
	v_pk_fma_f32 v[172:173], v[96:97], v[156:157], v[172:173]
	v_pk_fma_f32 v[174:175], v[90:91], v[158:159], v[174:175]
	v_pk_fma_f32 v[176:177], v[92:93], v[160:161], v[176:177]
	v_pk_mul_f32 v[170:171], v[150:151], v[170:171] op_sel_hi:[0,1]
	v_pk_mul_f32 v[172:173], v[150:151], v[172:173] op_sel_hi:[0,1]
	v_pk_mul_f32 v[174:175], v[150:151], v[174:175] op_sel_hi:[0,1]
	v_pk_mul_f32 v[176:177], v[150:151], v[176:177] op_sel_hi:[0,1]
	v_cvt_pk_bf16_f32 v170, v170, v171
	v_cvt_pk_bf16_f32 v171, v172, v173
	v_cvt_pk_bf16_f32 v172, v174, v175
	v_cvt_pk_bf16_f32 v173, v176, v177
	global_store_dwordx4 v[132:133], v[170:173], off
	v_lshl_add_u64 v[130:131], v[130:131], 0, s[6:7]
	global_load_dwordx4 v[126:129], v[134:135], off offset:1024
	global_load_dwordx4 v[122:125], v[134:135], off offset:1040
	global_load_dwordx4 v[94:97], v[134:135], off offset:1056
	global_load_dwordx4 v[90:93], v[134:135], off offset:1072
	global_load_dwordx4 v[154:157], v[134:135], off offset:2048
	global_load_dwordx4 v[158:161], v[134:135], off offset:2064
	global_load_dwordx4 v[162:165], v[134:135], off offset:2080
	global_load_dwordx4 v[166:169], v[134:135], off offset:2096
	s_waitcnt vmcnt(4)
	v_cndmask_b32_e64 v126, 1.0, v126, s[76:77]
	v_cndmask_b32_e64 v127, 1.0, v127, s[76:77]
	v_cndmask_b32_e64 v128, 1.0, v128, s[76:77]
	v_cndmask_b32_e64 v129, 1.0, v129, s[76:77]
	v_cndmask_b32_e64 v122, 1.0, v122, s[76:77]
	v_cndmask_b32_e64 v123, 1.0, v123, s[76:77]
	v_cndmask_b32_e64 v124, 1.0, v124, s[76:77]
	v_cndmask_b32_e64 v125, 1.0, v125, s[76:77]
	v_pk_mul_f32 v[94:95], v[152:153], v[94:95] op_sel_hi:[0,1]
	v_pk_mul_f32 v[96:97], v[152:153], v[96:97] op_sel_hi:[0,1]
	v_pk_mul_f32 v[90:91], v[152:153], v[90:91] op_sel_hi:[0,1]
	v_pk_mul_f32 v[92:93], v[152:153], v[92:93] op_sel_hi:[0,1]
	ds_bpermute_b32 v170, v0, v118
	ds_bpermute_b32 v171, v0, v119
	ds_bpermute_b32 v172, v0, v120
	ds_bpermute_b32 v173, v0, v121
	ds_bpermute_b32 v174, v0, v114
	ds_bpermute_b32 v175, v0, v115
	ds_bpermute_b32 v176, v0, v116
	ds_bpermute_b32 v177, v0, v117
	s_waitcnt lgkmcnt(0)
	v_pk_mul_f32 v[170:171], v[94:95], v[170:171]
	v_pk_mul_f32 v[172:173], v[96:97], v[172:173]
	v_pk_mul_f32 v[174:175], v[90:91], v[174:175]
	v_pk_mul_f32 v[176:177], v[92:93], v[176:177]
	v_pk_fma_f32 v[170:171], v[118:119], v[126:127], v[170:171]
	v_pk_fma_f32 v[172:173], v[120:121], v[128:129], v[172:173]
	v_pk_fma_f32 v[174:175], v[114:115], v[122:123], v[174:175]
	v_pk_fma_f32 v[176:177], v[116:117], v[124:125], v[176:177]
	v_pk_mul_f32 v[170:171], v[150:151], v[170:171] op_sel_hi:[0,1]
	v_pk_mul_f32 v[172:173], v[150:151], v[172:173] op_sel_hi:[0,1]
	v_pk_mul_f32 v[174:175], v[150:151], v[174:175] op_sel_hi:[0,1]
	v_pk_mul_f32 v[176:177], v[150:151], v[176:177] op_sel_hi:[0,1]
	v_cvt_pk_bf16_f32 v170, v170, v171
	v_cvt_pk_bf16_f32 v171, v172, v173
	v_cvt_pk_bf16_f32 v172, v174, v175
	v_cvt_pk_bf16_f32 v173, v176, v177
	global_store_dwordx4 v[130:131], v[170:173], off
	v_lshl_add_u64 v[132:133], v[130:131], 0, s[80:81]
	ds_bpermute_b32 v170, v0, v86
	ds_bpermute_b32 v171, v0, v87
	ds_bpermute_b32 v172, v0, v88
	ds_bpermute_b32 v173, v0, v89
	ds_bpermute_b32 v174, v0, v82
	ds_bpermute_b32 v175, v0, v83
	ds_bpermute_b32 v176, v0, v84
	ds_bpermute_b32 v177, v0, v85
	s_waitcnt lgkmcnt(0)
	v_pk_mul_f32 v[170:171], v[94:95], v[170:171]
	v_pk_mul_f32 v[172:173], v[96:97], v[172:173]
	v_pk_mul_f32 v[174:175], v[90:91], v[174:175]
	v_pk_mul_f32 v[176:177], v[92:93], v[176:177]
	v_pk_fma_f32 v[170:171], v[86:87], v[126:127], v[170:171]
	v_pk_fma_f32 v[172:173], v[88:89], v[128:129], v[172:173]
	v_pk_fma_f32 v[174:175], v[82:83], v[122:123], v[174:175]
	v_pk_fma_f32 v[176:177], v[84:85], v[124:125], v[176:177]
	v_pk_mul_f32 v[170:171], v[150:151], v[170:171] op_sel_hi:[0,1]
	v_pk_mul_f32 v[172:173], v[150:151], v[172:173] op_sel_hi:[0,1]
	v_pk_mul_f32 v[174:175], v[150:151], v[174:175] op_sel_hi:[0,1]
	v_pk_mul_f32 v[176:177], v[150:151], v[176:177] op_sel_hi:[0,1]
	v_cvt_pk_bf16_f32 v170, v170, v171
	v_cvt_pk_bf16_f32 v171, v172, v173
	v_cvt_pk_bf16_f32 v172, v174, v175
	v_cvt_pk_bf16_f32 v173, v176, v177
	global_store_dwordx4 v[132:133], v[170:173], off
	v_lshl_add_u64 v[130:131], v[130:131], 0, s[6:7]
	global_load_dwordx4 v[126:129], v[134:135], off offset:3072
	global_load_dwordx4 v[122:125], v[134:135], off offset:3088
	global_load_dwordx4 v[94:97], v[134:135], off offset:3104
	global_load_dwordx4 v[90:93], v[134:135], off offset:3120
	s_waitcnt vmcnt(6)
	v_cndmask_b32_e64 v154, 1.0, v154, s[76:77]
	v_cndmask_b32_e64 v155, 1.0, v155, s[76:77]
	v_cndmask_b32_e64 v156, 1.0, v156, s[76:77]
	v_cndmask_b32_e64 v157, 1.0, v157, s[76:77]
	v_cndmask_b32_e64 v158, 1.0, v158, s[76:77]
	v_cndmask_b32_e64 v159, 1.0, v159, s[76:77]
	v_cndmask_b32_e64 v160, 1.0, v160, s[76:77]
	v_cndmask_b32_e64 v161, 1.0, v161, s[76:77]
	v_pk_mul_f32 v[162:163], v[152:153], v[162:163] op_sel_hi:[0,1]
	v_pk_mul_f32 v[164:165], v[152:153], v[164:165] op_sel_hi:[0,1]
	v_pk_mul_f32 v[166:167], v[152:153], v[166:167] op_sel_hi:[0,1]
	v_pk_mul_f32 v[168:169], v[152:153], v[168:169] op_sel_hi:[0,1]
	ds_bpermute_b32 v170, v0, v110
	ds_bpermute_b32 v171, v0, v111
	ds_bpermute_b32 v172, v0, v112
	ds_bpermute_b32 v173, v0, v113
	ds_bpermute_b32 v174, v0, v106
	ds_bpermute_b32 v175, v0, v107
	ds_bpermute_b32 v176, v0, v108
	ds_bpermute_b32 v177, v0, v109
	s_waitcnt lgkmcnt(0)
	v_pk_mul_f32 v[170:171], v[162:163], v[170:171]
	v_pk_mul_f32 v[172:173], v[164:165], v[172:173]
	v_pk_mul_f32 v[174:175], v[166:167], v[174:175]
	v_pk_mul_f32 v[176:177], v[168:169], v[176:177]
	v_pk_fma_f32 v[170:171], v[110:111], v[154:155], v[170:171]
	v_pk_fma_f32 v[172:173], v[112:113], v[156:157], v[172:173]
	v_pk_fma_f32 v[174:175], v[106:107], v[158:159], v[174:175]
	v_pk_fma_f32 v[176:177], v[108:109], v[160:161], v[176:177]
	v_pk_mul_f32 v[170:171], v[150:151], v[170:171] op_sel_hi:[0,1]
	v_pk_mul_f32 v[172:173], v[150:151], v[172:173] op_sel_hi:[0,1]
	v_pk_mul_f32 v[174:175], v[150:151], v[174:175] op_sel_hi:[0,1]
	v_pk_mul_f32 v[176:177], v[150:151], v[176:177] op_sel_hi:[0,1]
	v_cvt_pk_bf16_f32 v170, v170, v171
	v_cvt_pk_bf16_f32 v171, v172, v173
	v_cvt_pk_bf16_f32 v172, v174, v175
	v_cvt_pk_bf16_f32 v173, v176, v177
	global_store_dwordx4 v[130:131], v[170:173], off
	v_lshl_add_u64 v[132:133], v[130:131], 0, s[80:81]
	ds_bpermute_b32 v170, v0, v78
	ds_bpermute_b32 v171, v0, v79
	ds_bpermute_b32 v172, v0, v80
	ds_bpermute_b32 v173, v0, v81
	ds_bpermute_b32 v174, v0, v74
	ds_bpermute_b32 v175, v0, v75
	ds_bpermute_b32 v176, v0, v76
	ds_bpermute_b32 v177, v0, v77
	s_waitcnt lgkmcnt(0)
	v_pk_mul_f32 v[170:171], v[162:163], v[170:171]
	v_pk_mul_f32 v[172:173], v[164:165], v[172:173]
	v_pk_mul_f32 v[174:175], v[166:167], v[174:175]
	v_pk_mul_f32 v[176:177], v[168:169], v[176:177]
	v_pk_fma_f32 v[170:171], v[78:79], v[154:155], v[170:171]
	v_pk_fma_f32 v[172:173], v[80:81], v[156:157], v[172:173]
	v_pk_fma_f32 v[174:175], v[74:75], v[158:159], v[174:175]
	v_pk_fma_f32 v[176:177], v[76:77], v[160:161], v[176:177]
	v_pk_mul_f32 v[170:171], v[150:151], v[170:171] op_sel_hi:[0,1]
	v_pk_mul_f32 v[172:173], v[150:151], v[172:173] op_sel_hi:[0,1]
	v_pk_mul_f32 v[174:175], v[150:151], v[174:175] op_sel_hi:[0,1]
	v_pk_mul_f32 v[176:177], v[150:151], v[176:177] op_sel_hi:[0,1]
	v_cvt_pk_bf16_f32 v170, v170, v171
	v_cvt_pk_bf16_f32 v171, v172, v173
	v_cvt_pk_bf16_f32 v172, v174, v175
	v_cvt_pk_bf16_f32 v173, v176, v177
	global_store_dwordx4 v[132:133], v[170:173], off
	v_lshl_add_u64 v[130:131], v[130:131], 0, s[6:7]
	global_load_dwordx4 v[154:157], v[136:137], off offset:0
	global_load_dwordx4 v[158:161], v[136:137], off offset:16
	global_load_dwordx4 v[162:165], v[136:137], off offset:32
	global_load_dwordx4 v[166:169], v[136:137], off offset:48
	s_waitcnt vmcnt(6)
	v_cndmask_b32_e64 v126, 1.0, v126, s[76:77]
	v_cndmask_b32_e64 v127, 1.0, v127, s[76:77]
	v_cndmask_b32_e64 v128, 1.0, v128, s[76:77]
	v_cndmask_b32_e64 v129, 1.0, v129, s[76:77]
	v_cndmask_b32_e64 v122, 1.0, v122, s[76:77]
	v_cndmask_b32_e64 v123, 1.0, v123, s[76:77]
	v_cndmask_b32_e64 v124, 1.0, v124, s[76:77]
	v_cndmask_b32_e64 v125, 1.0, v125, s[76:77]
	v_pk_mul_f32 v[94:95], v[152:153], v[94:95] op_sel_hi:[0,1]
	v_pk_mul_f32 v[96:97], v[152:153], v[96:97] op_sel_hi:[0,1]
	v_pk_mul_f32 v[90:91], v[152:153], v[90:91] op_sel_hi:[0,1]
	v_pk_mul_f32 v[92:93], v[152:153], v[92:93] op_sel_hi:[0,1]
	ds_bpermute_b32 v170, v0, v102
	ds_bpermute_b32 v171, v0, v103
	ds_bpermute_b32 v172, v0, v104
	ds_bpermute_b32 v173, v0, v105
	ds_bpermute_b32 v174, v0, v98
	ds_bpermute_b32 v175, v0, v99
	ds_bpermute_b32 v176, v0, v100
	ds_bpermute_b32 v177, v0, v101
	s_waitcnt lgkmcnt(0)
	v_pk_mul_f32 v[170:171], v[94:95], v[170:171]
	v_pk_mul_f32 v[172:173], v[96:97], v[172:173]
	v_pk_mul_f32 v[174:175], v[90:91], v[174:175]
	v_pk_mul_f32 v[176:177], v[92:93], v[176:177]
	v_pk_fma_f32 v[170:171], v[102:103], v[126:127], v[170:171]
	v_pk_fma_f32 v[172:173], v[104:105], v[128:129], v[172:173]
	v_pk_fma_f32 v[174:175], v[98:99], v[122:123], v[174:175]
	v_pk_fma_f32 v[176:177], v[100:101], v[124:125], v[176:177]
	v_pk_mul_f32 v[170:171], v[150:151], v[170:171] op_sel_hi:[0,1]
	v_pk_mul_f32 v[172:173], v[150:151], v[172:173] op_sel_hi:[0,1]
	v_pk_mul_f32 v[174:175], v[150:151], v[174:175] op_sel_hi:[0,1]
	v_pk_mul_f32 v[176:177], v[150:151], v[176:177] op_sel_hi:[0,1]
	v_cvt_pk_bf16_f32 v170, v170, v171
	v_cvt_pk_bf16_f32 v171, v172, v173
	v_cvt_pk_bf16_f32 v172, v174, v175
	v_cvt_pk_bf16_f32 v173, v176, v177
	global_store_dwordx4 v[130:131], v[170:173], off
	v_lshl_add_u64 v[132:133], v[130:131], 0, s[80:81]
	ds_bpermute_b32 v170, v0, v70
	ds_bpermute_b32 v171, v0, v71
	ds_bpermute_b32 v172, v0, v72
	ds_bpermute_b32 v173, v0, v73
	ds_bpermute_b32 v174, v0, v66
	ds_bpermute_b32 v175, v0, v67
	ds_bpermute_b32 v176, v0, v68
	ds_bpermute_b32 v177, v0, v69
	s_waitcnt lgkmcnt(0)
	v_pk_mul_f32 v[170:171], v[94:95], v[170:171]
	v_pk_mul_f32 v[172:173], v[96:97], v[172:173]
	v_pk_mul_f32 v[174:175], v[90:91], v[174:175]
	v_pk_mul_f32 v[176:177], v[92:93], v[176:177]
	v_pk_fma_f32 v[170:171], v[70:71], v[126:127], v[170:171]
	v_pk_fma_f32 v[172:173], v[72:73], v[128:129], v[172:173]
	v_pk_fma_f32 v[174:175], v[66:67], v[122:123], v[174:175]
	v_pk_fma_f32 v[176:177], v[68:69], v[124:125], v[176:177]
	v_pk_mul_f32 v[170:171], v[150:151], v[170:171] op_sel_hi:[0,1]
	v_pk_mul_f32 v[172:173], v[150:151], v[172:173] op_sel_hi:[0,1]
	v_pk_mul_f32 v[174:175], v[150:151], v[174:175] op_sel_hi:[0,1]
	v_pk_mul_f32 v[176:177], v[150:151], v[176:177] op_sel_hi:[0,1]
	v_cvt_pk_bf16_f32 v170, v170, v171
	v_cvt_pk_bf16_f32 v171, v172, v173
	v_cvt_pk_bf16_f32 v172, v174, v175
	v_cvt_pk_bf16_f32 v173, v176, v177
	global_store_dwordx4 v[132:133], v[170:173], off
	v_lshl_add_u64 v[130:131], v[130:131], 0, s[0:1]
	global_load_dwordx4 v[126:129], v[136:137], off offset:1024
	global_load_dwordx4 v[122:125], v[136:137], off offset:1040
	global_load_dwordx4 v[94:97], v[136:137], off offset:1056
	global_load_dwordx4 v[90:93], v[136:137], off offset:1072
	s_waitcnt vmcnt(6)
	v_cndmask_b32_e64 v154, 1.0, v154, s[76:77]
	v_cndmask_b32_e64 v155, 1.0, v155, s[76:77]
	v_cndmask_b32_e64 v156, 1.0, v156, s[76:77]
	v_cndmask_b32_e64 v157, 1.0, v157, s[76:77]
	v_cndmask_b32_e64 v158, 1.0, v158, s[76:77]
	v_cndmask_b32_e64 v159, 1.0, v159, s[76:77]
	v_cndmask_b32_e64 v160, 1.0, v160, s[76:77]
	v_cndmask_b32_e64 v161, 1.0, v161, s[76:77]
	v_pk_mul_f32 v[162:163], v[152:153], v[162:163] op_sel_hi:[0,1]
	v_pk_mul_f32 v[164:165], v[152:153], v[164:165] op_sel_hi:[0,1]
	v_pk_mul_f32 v[166:167], v[152:153], v[166:167] op_sel_hi:[0,1]
	v_pk_mul_f32 v[168:169], v[152:153], v[168:169] op_sel_hi:[0,1]
	ds_bpermute_b32 v170, v0, v62
	ds_bpermute_b32 v171, v0, v63
	ds_bpermute_b32 v172, v0, v64
	ds_bpermute_b32 v173, v0, v65
	ds_bpermute_b32 v174, v0, v58
	ds_bpermute_b32 v175, v0, v59
	ds_bpermute_b32 v176, v0, v60
	ds_bpermute_b32 v177, v0, v61
	s_waitcnt lgkmcnt(0)
	v_pk_mul_f32 v[170:171], v[162:163], v[170:171]
	v_pk_mul_f32 v[172:173], v[164:165], v[172:173]
	v_pk_mul_f32 v[174:175], v[166:167], v[174:175]
	v_pk_mul_f32 v[176:177], v[168:169], v[176:177]
	v_pk_fma_f32 v[170:171], v[62:63], v[154:155], v[170:171]
	v_pk_fma_f32 v[172:173], v[64:65], v[156:157], v[172:173]
	v_pk_fma_f32 v[174:175], v[58:59], v[158:159], v[174:175]
	v_pk_fma_f32 v[176:177], v[60:61], v[160:161], v[176:177]
	v_pk_mul_f32 v[170:171], v[150:151], v[170:171] op_sel_hi:[0,1]
	v_pk_mul_f32 v[172:173], v[150:151], v[172:173] op_sel_hi:[0,1]
	v_pk_mul_f32 v[174:175], v[150:151], v[174:175] op_sel_hi:[0,1]
	v_pk_mul_f32 v[176:177], v[150:151], v[176:177] op_sel_hi:[0,1]
	v_cvt_pk_bf16_f32 v170, v170, v171
	v_cvt_pk_bf16_f32 v171, v172, v173
	v_cvt_pk_bf16_f32 v172, v174, v175
	v_cvt_pk_bf16_f32 v173, v176, v177
	global_store_dwordx4 v[130:131], v[170:173], off
	v_lshl_add_u64 v[132:133], v[130:131], 0, s[80:81]
	ds_bpermute_b32 v170, v0, v30
	ds_bpermute_b32 v171, v0, v31
	ds_bpermute_b32 v172, v0, v32
	ds_bpermute_b32 v173, v0, v33
	ds_bpermute_b32 v174, v0, v26
	ds_bpermute_b32 v175, v0, v27
	ds_bpermute_b32 v176, v0, v28
	ds_bpermute_b32 v177, v0, v29
	s_waitcnt lgkmcnt(0)
	v_pk_mul_f32 v[170:171], v[162:163], v[170:171]
	v_pk_mul_f32 v[172:173], v[164:165], v[172:173]
	v_pk_mul_f32 v[174:175], v[166:167], v[174:175]
	v_pk_mul_f32 v[176:177], v[168:169], v[176:177]
	v_pk_fma_f32 v[170:171], v[30:31], v[154:155], v[170:171]
	v_pk_fma_f32 v[172:173], v[32:33], v[156:157], v[172:173]
	v_pk_fma_f32 v[174:175], v[26:27], v[158:159], v[174:175]
	v_pk_fma_f32 v[176:177], v[28:29], v[160:161], v[176:177]
	v_pk_mul_f32 v[170:171], v[150:151], v[170:171] op_sel_hi:[0,1]
	v_pk_mul_f32 v[172:173], v[150:151], v[172:173] op_sel_hi:[0,1]
	v_pk_mul_f32 v[174:175], v[150:151], v[174:175] op_sel_hi:[0,1]
	v_pk_mul_f32 v[176:177], v[150:151], v[176:177] op_sel_hi:[0,1]
	v_cvt_pk_bf16_f32 v170, v170, v171
	v_cvt_pk_bf16_f32 v171, v172, v173
	v_cvt_pk_bf16_f32 v172, v174, v175
	v_cvt_pk_bf16_f32 v173, v176, v177
	global_store_dwordx4 v[132:133], v[170:173], off
	v_lshl_add_u64 v[130:131], v[130:131], 0, s[6:7]
	global_load_dwordx4 v[154:157], v[136:137], off offset:2048
	global_load_dwordx4 v[158:161], v[136:137], off offset:2064
	global_load_dwordx4 v[162:165], v[136:137], off offset:2080
	global_load_dwordx4 v[166:169], v[136:137], off offset:2096
	s_waitcnt vmcnt(6)
	v_cndmask_b32_e64 v126, 1.0, v126, s[76:77]
	v_cndmask_b32_e64 v127, 1.0, v127, s[76:77]
	v_cndmask_b32_e64 v128, 1.0, v128, s[76:77]
	v_cndmask_b32_e64 v129, 1.0, v129, s[76:77]
	v_cndmask_b32_e64 v122, 1.0, v122, s[76:77]
	v_cndmask_b32_e64 v123, 1.0, v123, s[76:77]
	v_cndmask_b32_e64 v124, 1.0, v124, s[76:77]
	v_cndmask_b32_e64 v125, 1.0, v125, s[76:77]
	v_pk_mul_f32 v[94:95], v[152:153], v[94:95] op_sel_hi:[0,1]
	v_pk_mul_f32 v[96:97], v[152:153], v[96:97] op_sel_hi:[0,1]
	v_pk_mul_f32 v[90:91], v[152:153], v[90:91] op_sel_hi:[0,1]
	v_pk_mul_f32 v[92:93], v[152:153], v[92:93] op_sel_hi:[0,1]
	ds_bpermute_b32 v170, v0, v54
	ds_bpermute_b32 v171, v0, v55
	ds_bpermute_b32 v172, v0, v56
	ds_bpermute_b32 v173, v0, v57
	ds_bpermute_b32 v174, v0, v50
	ds_bpermute_b32 v175, v0, v51
	ds_bpermute_b32 v176, v0, v52
	ds_bpermute_b32 v177, v0, v53
	s_waitcnt lgkmcnt(0)
	v_pk_mul_f32 v[170:171], v[94:95], v[170:171]
	v_pk_mul_f32 v[172:173], v[96:97], v[172:173]
	v_pk_mul_f32 v[174:175], v[90:91], v[174:175]
	v_pk_mul_f32 v[176:177], v[92:93], v[176:177]
	v_pk_fma_f32 v[170:171], v[54:55], v[126:127], v[170:171]
	v_pk_fma_f32 v[172:173], v[56:57], v[128:129], v[172:173]
	v_pk_fma_f32 v[174:175], v[50:51], v[122:123], v[174:175]
	v_pk_fma_f32 v[176:177], v[52:53], v[124:125], v[176:177]
	v_pk_mul_f32 v[170:171], v[150:151], v[170:171] op_sel_hi:[0,1]
	v_pk_mul_f32 v[172:173], v[150:151], v[172:173] op_sel_hi:[0,1]
	v_pk_mul_f32 v[174:175], v[150:151], v[174:175] op_sel_hi:[0,1]
	v_pk_mul_f32 v[176:177], v[150:151], v[176:177] op_sel_hi:[0,1]
	v_cvt_pk_bf16_f32 v170, v170, v171
	v_cvt_pk_bf16_f32 v171, v172, v173
	v_cvt_pk_bf16_f32 v172, v174, v175
	v_cvt_pk_bf16_f32 v173, v176, v177
	global_store_dwordx4 v[130:131], v[170:173], off
	v_lshl_add_u64 v[132:133], v[130:131], 0, s[80:81]
	ds_bpermute_b32 v170, v0, v22
	ds_bpermute_b32 v171, v0, v23
	ds_bpermute_b32 v172, v0, v24
	ds_bpermute_b32 v173, v0, v25
	ds_bpermute_b32 v174, v0, v18
	ds_bpermute_b32 v175, v0, v19
	ds_bpermute_b32 v176, v0, v20
	ds_bpermute_b32 v177, v0, v21
	s_waitcnt lgkmcnt(0)
	v_pk_mul_f32 v[170:171], v[94:95], v[170:171]
	v_pk_mul_f32 v[172:173], v[96:97], v[172:173]
	v_pk_mul_f32 v[174:175], v[90:91], v[174:175]
	v_pk_mul_f32 v[176:177], v[92:93], v[176:177]
	v_pk_fma_f32 v[170:171], v[22:23], v[126:127], v[170:171]
	v_pk_fma_f32 v[172:173], v[24:25], v[128:129], v[172:173]
	v_pk_fma_f32 v[174:175], v[18:19], v[122:123], v[174:175]
	v_pk_fma_f32 v[176:177], v[20:21], v[124:125], v[176:177]
	v_pk_mul_f32 v[170:171], v[150:151], v[170:171] op_sel_hi:[0,1]
	v_pk_mul_f32 v[172:173], v[150:151], v[172:173] op_sel_hi:[0,1]
	v_pk_mul_f32 v[174:175], v[150:151], v[174:175] op_sel_hi:[0,1]
	v_pk_mul_f32 v[176:177], v[150:151], v[176:177] op_sel_hi:[0,1]
	v_cvt_pk_bf16_f32 v170, v170, v171
	v_cvt_pk_bf16_f32 v171, v172, v173
	v_cvt_pk_bf16_f32 v172, v174, v175
	v_cvt_pk_bf16_f32 v173, v176, v177
	global_store_dwordx4 v[132:133], v[170:173], off
	v_lshl_add_u64 v[130:131], v[130:131], 0, s[6:7]
	global_load_dwordx4 v[126:129], v[136:137], off offset:3072
	global_load_dwordx4 v[122:125], v[136:137], off offset:3088
	global_load_dwordx4 v[94:97], v[136:137], off offset:3104
	global_load_dwordx4 v[90:93], v[136:137], off offset:3120
	s_waitcnt vmcnt(6)
	v_cndmask_b32_e64 v154, 1.0, v154, s[76:77]
	v_cndmask_b32_e64 v155, 1.0, v155, s[76:77]
	v_cndmask_b32_e64 v156, 1.0, v156, s[76:77]
	v_cndmask_b32_e64 v157, 1.0, v157, s[76:77]
	v_cndmask_b32_e64 v158, 1.0, v158, s[76:77]
	v_cndmask_b32_e64 v159, 1.0, v159, s[76:77]
	v_cndmask_b32_e64 v160, 1.0, v160, s[76:77]
	v_cndmask_b32_e64 v161, 1.0, v161, s[76:77]
	v_pk_mul_f32 v[162:163], v[152:153], v[162:163] op_sel_hi:[0,1]
	v_pk_mul_f32 v[164:165], v[152:153], v[164:165] op_sel_hi:[0,1]
	v_pk_mul_f32 v[166:167], v[152:153], v[166:167] op_sel_hi:[0,1]
	v_pk_mul_f32 v[168:169], v[152:153], v[168:169] op_sel_hi:[0,1]
	ds_bpermute_b32 v170, v0, v46
	ds_bpermute_b32 v171, v0, v47
	ds_bpermute_b32 v172, v0, v48
	ds_bpermute_b32 v173, v0, v49
	ds_bpermute_b32 v174, v0, v42
	ds_bpermute_b32 v175, v0, v43
	ds_bpermute_b32 v176, v0, v44
	ds_bpermute_b32 v177, v0, v45
	s_waitcnt lgkmcnt(0)
	v_pk_mul_f32 v[170:171], v[162:163], v[170:171]
	v_pk_mul_f32 v[172:173], v[164:165], v[172:173]
	v_pk_mul_f32 v[174:175], v[166:167], v[174:175]
	v_pk_mul_f32 v[176:177], v[168:169], v[176:177]
	v_pk_fma_f32 v[170:171], v[46:47], v[154:155], v[170:171]
	v_pk_fma_f32 v[172:173], v[48:49], v[156:157], v[172:173]
	v_pk_fma_f32 v[174:175], v[42:43], v[158:159], v[174:175]
	v_pk_fma_f32 v[176:177], v[44:45], v[160:161], v[176:177]
	v_pk_mul_f32 v[170:171], v[150:151], v[170:171] op_sel_hi:[0,1]
	v_pk_mul_f32 v[172:173], v[150:151], v[172:173] op_sel_hi:[0,1]
	v_pk_mul_f32 v[174:175], v[150:151], v[174:175] op_sel_hi:[0,1]
	v_pk_mul_f32 v[176:177], v[150:151], v[176:177] op_sel_hi:[0,1]
	v_cvt_pk_bf16_f32 v170, v170, v171
	v_cvt_pk_bf16_f32 v171, v172, v173
	v_cvt_pk_bf16_f32 v172, v174, v175
	v_cvt_pk_bf16_f32 v173, v176, v177
	global_store_dwordx4 v[130:131], v[170:173], off
	v_lshl_add_u64 v[132:133], v[130:131], 0, s[80:81]
	ds_bpermute_b32 v170, v0, v14
	ds_bpermute_b32 v171, v0, v15
	ds_bpermute_b32 v172, v0, v16
	ds_bpermute_b32 v173, v0, v17
	ds_bpermute_b32 v174, v0, v10
	ds_bpermute_b32 v175, v0, v11
	ds_bpermute_b32 v176, v0, v12
	ds_bpermute_b32 v177, v0, v13
	s_waitcnt lgkmcnt(0)
	v_pk_mul_f32 v[170:171], v[162:163], v[170:171]
	v_pk_mul_f32 v[172:173], v[164:165], v[172:173]
	v_pk_mul_f32 v[174:175], v[166:167], v[174:175]
	v_pk_mul_f32 v[176:177], v[168:169], v[176:177]
	v_pk_fma_f32 v[170:171], v[14:15], v[154:155], v[170:171]
	v_pk_fma_f32 v[172:173], v[16:17], v[156:157], v[172:173]
	v_pk_fma_f32 v[174:175], v[10:11], v[158:159], v[174:175]
	v_pk_fma_f32 v[176:177], v[12:13], v[160:161], v[176:177]
	v_pk_mul_f32 v[170:171], v[150:151], v[170:171] op_sel_hi:[0,1]
	v_pk_mul_f32 v[172:173], v[150:151], v[172:173] op_sel_hi:[0,1]
	v_pk_mul_f32 v[174:175], v[150:151], v[174:175] op_sel_hi:[0,1]
	v_pk_mul_f32 v[176:177], v[150:151], v[176:177] op_sel_hi:[0,1]
	v_cvt_pk_bf16_f32 v170, v170, v171
	v_cvt_pk_bf16_f32 v171, v172, v173
	v_cvt_pk_bf16_f32 v172, v174, v175
	v_cvt_pk_bf16_f32 v173, v176, v177
	global_store_dwordx4 v[132:133], v[170:173], off
	v_lshl_add_u64 v[130:131], v[130:131], 0, s[6:7]
	s_waitcnt vmcnt(2)
	v_cndmask_b32_e64 v126, 1.0, v126, s[76:77]
	v_cndmask_b32_e64 v127, 1.0, v127, s[76:77]
	v_cndmask_b32_e64 v128, 1.0, v128, s[76:77]
	v_cndmask_b32_e64 v129, 1.0, v129, s[76:77]
	v_cndmask_b32_e64 v122, 1.0, v122, s[76:77]
	v_cndmask_b32_e64 v123, 1.0, v123, s[76:77]
	v_cndmask_b32_e64 v124, 1.0, v124, s[76:77]
	v_cndmask_b32_e64 v125, 1.0, v125, s[76:77]
	v_pk_mul_f32 v[94:95], v[152:153], v[94:95] op_sel_hi:[0,1]
	v_pk_mul_f32 v[96:97], v[152:153], v[96:97] op_sel_hi:[0,1]
	v_pk_mul_f32 v[90:91], v[152:153], v[90:91] op_sel_hi:[0,1]
	v_pk_mul_f32 v[92:93], v[152:153], v[92:93] op_sel_hi:[0,1]
	ds_bpermute_b32 v170, v0, v38
	ds_bpermute_b32 v171, v0, v39
	ds_bpermute_b32 v172, v0, v40
	ds_bpermute_b32 v173, v0, v41
	ds_bpermute_b32 v174, v0, v34
	ds_bpermute_b32 v175, v0, v35
	ds_bpermute_b32 v176, v0, v36
	ds_bpermute_b32 v177, v0, v37
	s_waitcnt lgkmcnt(0)
	v_pk_mul_f32 v[170:171], v[94:95], v[170:171]
	v_pk_mul_f32 v[172:173], v[96:97], v[172:173]
	v_pk_mul_f32 v[174:175], v[90:91], v[174:175]
	v_pk_mul_f32 v[176:177], v[92:93], v[176:177]
	v_pk_fma_f32 v[170:171], v[38:39], v[126:127], v[170:171]
	v_pk_fma_f32 v[172:173], v[40:41], v[128:129], v[172:173]
	v_pk_fma_f32 v[174:175], v[34:35], v[122:123], v[174:175]
	v_pk_fma_f32 v[176:177], v[36:37], v[124:125], v[176:177]
	v_pk_mul_f32 v[170:171], v[150:151], v[170:171] op_sel_hi:[0,1]
	v_pk_mul_f32 v[172:173], v[150:151], v[172:173] op_sel_hi:[0,1]
	v_pk_mul_f32 v[174:175], v[150:151], v[174:175] op_sel_hi:[0,1]
	v_pk_mul_f32 v[176:177], v[150:151], v[176:177] op_sel_hi:[0,1]
	v_cvt_pk_bf16_f32 v170, v170, v171
	v_cvt_pk_bf16_f32 v171, v172, v173
	v_cvt_pk_bf16_f32 v172, v174, v175
	v_cvt_pk_bf16_f32 v173, v176, v177
	global_store_dwordx4 v[130:131], v[170:173], off
	v_lshl_add_u64 v[132:133], v[130:131], 0, s[80:81]
	ds_bpermute_b32 v170, v0, v6
	ds_bpermute_b32 v171, v0, v7
	ds_bpermute_b32 v172, v0, v8
	ds_bpermute_b32 v173, v0, v9
	ds_bpermute_b32 v174, v0, v2
	ds_bpermute_b32 v175, v0, v3
	ds_bpermute_b32 v176, v0, v4
	ds_bpermute_b32 v177, v0, v5
	s_waitcnt lgkmcnt(0)
	v_pk_mul_f32 v[170:171], v[94:95], v[170:171]
	v_pk_mul_f32 v[172:173], v[96:97], v[172:173]
	v_pk_mul_f32 v[174:175], v[90:91], v[174:175]
	v_pk_mul_f32 v[176:177], v[92:93], v[176:177]
	v_pk_fma_f32 v[170:171], v[6:7], v[126:127], v[170:171]
	v_pk_fma_f32 v[172:173], v[8:9], v[128:129], v[172:173]
	v_pk_fma_f32 v[174:175], v[2:3], v[122:123], v[174:175]
	v_pk_fma_f32 v[176:177], v[4:5], v[124:125], v[176:177]
	v_pk_mul_f32 v[170:171], v[150:151], v[170:171] op_sel_hi:[0,1]
	v_pk_mul_f32 v[172:173], v[150:151], v[172:173] op_sel_hi:[0,1]
	v_pk_mul_f32 v[174:175], v[150:151], v[174:175] op_sel_hi:[0,1]
	v_pk_mul_f32 v[176:177], v[150:151], v[176:177] op_sel_hi:[0,1]
	v_cvt_pk_bf16_f32 v170, v170, v171
	v_cvt_pk_bf16_f32 v171, v172, v173
	v_cvt_pk_bf16_f32 v172, v174, v175
	v_cvt_pk_bf16_f32 v173, v176, v177
	global_store_dwordx4 v[132:133], v[170:173], off
	s_branch .Lqk_done
.Lqk_nonrot:
	v_pk_mul_f32 v[170:171], v[150:151], v[126:127] op_sel_hi:[0,1]
	v_pk_mul_f32 v[172:173], v[150:151], v[128:129] op_sel_hi:[0,1]
	v_pk_mul_f32 v[174:175], v[150:151], v[122:123] op_sel_hi:[0,1]
	v_pk_mul_f32 v[176:177], v[150:151], v[124:125] op_sel_hi:[0,1]
	v_cvt_pk_bf16_f32 v170, v170, v171
	v_cvt_pk_bf16_f32 v171, v172, v173
	v_cvt_pk_bf16_f32 v172, v174, v175
	v_cvt_pk_bf16_f32 v173, v176, v177
	global_store_dwordx4 v[130:131], v[170:173], off
	v_lshl_add_u64 v[132:133], v[130:131], 0, s[80:81]
	s_nop 0
	v_pk_mul_f32 v[170:171], v[150:151], v[94:95] op_sel_hi:[0,1]
	v_pk_mul_f32 v[172:173], v[150:151], v[96:97] op_sel_hi:[0,1]
	v_pk_mul_f32 v[174:175], v[150:151], v[90:91] op_sel_hi:[0,1]
	v_pk_mul_f32 v[176:177], v[150:151], v[92:93] op_sel_hi:[0,1]
	v_cvt_pk_bf16_f32 v170, v170, v171
	v_cvt_pk_bf16_f32 v171, v172, v173
	v_cvt_pk_bf16_f32 v172, v174, v175
	v_cvt_pk_bf16_f32 v173, v176, v177
	global_store_dwordx4 v[132:133], v[170:173], off
	v_lshl_add_u64 v[130:131], v[130:131], 0, s[6:7]
	s_nop 0
	v_pk_mul_f32 v[170:171], v[150:151], v[118:119] op_sel_hi:[0,1]
	v_pk_mul_f32 v[172:173], v[150:151], v[120:121] op_sel_hi:[0,1]
	v_pk_mul_f32 v[174:175], v[150:151], v[114:115] op_sel_hi:[0,1]
	v_pk_mul_f32 v[176:177], v[150:151], v[116:117] op_sel_hi:[0,1]
	v_cvt_pk_bf16_f32 v170, v170, v171
	v_cvt_pk_bf16_f32 v171, v172, v173
	v_cvt_pk_bf16_f32 v172, v174, v175
	v_cvt_pk_bf16_f32 v173, v176, v177
	global_store_dwordx4 v[130:131], v[170:173], off
	v_lshl_add_u64 v[132:133], v[130:131], 0, s[80:81]
	s_nop 0
	v_pk_mul_f32 v[170:171], v[150:151], v[86:87] op_sel_hi:[0,1]
	v_pk_mul_f32 v[172:173], v[150:151], v[88:89] op_sel_hi:[0,1]
	v_pk_mul_f32 v[174:175], v[150:151], v[82:83] op_sel_hi:[0,1]
	v_pk_mul_f32 v[176:177], v[150:151], v[84:85] op_sel_hi:[0,1]
	v_cvt_pk_bf16_f32 v170, v170, v171
	v_cvt_pk_bf16_f32 v171, v172, v173
	v_cvt_pk_bf16_f32 v172, v174, v175
	v_cvt_pk_bf16_f32 v173, v176, v177
	global_store_dwordx4 v[132:133], v[170:173], off
	v_lshl_add_u64 v[130:131], v[130:131], 0, s[6:7]
	s_nop 0
	v_pk_mul_f32 v[170:171], v[150:151], v[110:111] op_sel_hi:[0,1]
	v_pk_mul_f32 v[172:173], v[150:151], v[112:113] op_sel_hi:[0,1]
	v_pk_mul_f32 v[174:175], v[150:151], v[106:107] op_sel_hi:[0,1]
	v_pk_mul_f32 v[176:177], v[150:151], v[108:109] op_sel_hi:[0,1]
	v_cvt_pk_bf16_f32 v170, v170, v171
	v_cvt_pk_bf16_f32 v171, v172, v173
	v_cvt_pk_bf16_f32 v172, v174, v175
	v_cvt_pk_bf16_f32 v173, v176, v177
	global_store_dwordx4 v[130:131], v[170:173], off
	v_lshl_add_u64 v[132:133], v[130:131], 0, s[80:81]
	s_nop 0
	v_pk_mul_f32 v[170:171], v[150:151], v[78:79] op_sel_hi:[0,1]
	v_pk_mul_f32 v[172:173], v[150:151], v[80:81] op_sel_hi:[0,1]
	v_pk_mul_f32 v[174:175], v[150:151], v[74:75] op_sel_hi:[0,1]
	v_pk_mul_f32 v[176:177], v[150:151], v[76:77] op_sel_hi:[0,1]
	v_cvt_pk_bf16_f32 v170, v170, v171
	v_cvt_pk_bf16_f32 v171, v172, v173
	v_cvt_pk_bf16_f32 v172, v174, v175
	v_cvt_pk_bf16_f32 v173, v176, v177
	global_store_dwordx4 v[132:133], v[170:173], off
	v_lshl_add_u64 v[130:131], v[130:131], 0, s[6:7]
	s_nop 0
	v_pk_mul_f32 v[170:171], v[150:151], v[102:103] op_sel_hi:[0,1]
	v_pk_mul_f32 v[172:173], v[150:151], v[104:105] op_sel_hi:[0,1]
	v_pk_mul_f32 v[174:175], v[150:151], v[98:99] op_sel_hi:[0,1]
	v_pk_mul_f32 v[176:177], v[150:151], v[100:101] op_sel_hi:[0,1]
	v_cvt_pk_bf16_f32 v170, v170, v171
	v_cvt_pk_bf16_f32 v171, v172, v173
	v_cvt_pk_bf16_f32 v172, v174, v175
	v_cvt_pk_bf16_f32 v173, v176, v177
	global_store_dwordx4 v[130:131], v[170:173], off
	v_lshl_add_u64 v[132:133], v[130:131], 0, s[80:81]
	s_nop 0
	v_pk_mul_f32 v[170:171], v[150:151], v[70:71] op_sel_hi:[0,1]
	v_pk_mul_f32 v[172:173], v[150:151], v[72:73] op_sel_hi:[0,1]
	v_pk_mul_f32 v[174:175], v[150:151], v[66:67] op_sel_hi:[0,1]
	v_pk_mul_f32 v[176:177], v[150:151], v[68:69] op_sel_hi:[0,1]
	v_cvt_pk_bf16_f32 v170, v170, v171
	v_cvt_pk_bf16_f32 v171, v172, v173
	v_cvt_pk_bf16_f32 v172, v174, v175
	v_cvt_pk_bf16_f32 v173, v176, v177
	global_store_dwordx4 v[132:133], v[170:173], off
	v_lshl_add_u64 v[130:131], v[130:131], 0, s[0:1]
	s_nop 0
	v_pk_mul_f32 v[170:171], v[150:151], v[62:63] op_sel_hi:[0,1]
	v_pk_mul_f32 v[172:173], v[150:151], v[64:65] op_sel_hi:[0,1]
	v_pk_mul_f32 v[174:175], v[150:151], v[58:59] op_sel_hi:[0,1]
	v_pk_mul_f32 v[176:177], v[150:151], v[60:61] op_sel_hi:[0,1]
	v_cvt_pk_bf16_f32 v170, v170, v171
	v_cvt_pk_bf16_f32 v171, v172, v173
	v_cvt_pk_bf16_f32 v172, v174, v175
	v_cvt_pk_bf16_f32 v173, v176, v177
	global_store_dwordx4 v[130:131], v[170:173], off
	v_lshl_add_u64 v[132:133], v[130:131], 0, s[80:81]
	s_nop 0
	v_pk_mul_f32 v[170:171], v[150:151], v[30:31] op_sel_hi:[0,1]
	v_pk_mul_f32 v[172:173], v[150:151], v[32:33] op_sel_hi:[0,1]
	v_pk_mul_f32 v[174:175], v[150:151], v[26:27] op_sel_hi:[0,1]
	v_pk_mul_f32 v[176:177], v[150:151], v[28:29] op_sel_hi:[0,1]
	v_cvt_pk_bf16_f32 v170, v170, v171
	v_cvt_pk_bf16_f32 v171, v172, v173
	v_cvt_pk_bf16_f32 v172, v174, v175
	v_cvt_pk_bf16_f32 v173, v176, v177
	global_store_dwordx4 v[132:133], v[170:173], off
	v_lshl_add_u64 v[130:131], v[130:131], 0, s[6:7]
	s_nop 0
	v_pk_mul_f32 v[170:171], v[150:151], v[54:55] op_sel_hi:[0,1]
	v_pk_mul_f32 v[172:173], v[150:151], v[56:57] op_sel_hi:[0,1]
	v_pk_mul_f32 v[174:175], v[150:151], v[50:51] op_sel_hi:[0,1]
	v_pk_mul_f32 v[176:177], v[150:151], v[52:53] op_sel_hi:[0,1]
	v_cvt_pk_bf16_f32 v170, v170, v171
	v_cvt_pk_bf16_f32 v171, v172, v173
	v_cvt_pk_bf16_f32 v172, v174, v175
	v_cvt_pk_bf16_f32 v173, v176, v177
	global_store_dwordx4 v[130:131], v[170:173], off
	v_lshl_add_u64 v[132:133], v[130:131], 0, s[80:81]
	s_nop 0
	v_pk_mul_f32 v[170:171], v[150:151], v[22:23] op_sel_hi:[0,1]
	v_pk_mul_f32 v[172:173], v[150:151], v[24:25] op_sel_hi:[0,1]
	v_pk_mul_f32 v[174:175], v[150:151], v[18:19] op_sel_hi:[0,1]
	v_pk_mul_f32 v[176:177], v[150:151], v[20:21] op_sel_hi:[0,1]
	v_cvt_pk_bf16_f32 v170, v170, v171
	v_cvt_pk_bf16_f32 v171, v172, v173
	v_cvt_pk_bf16_f32 v172, v174, v175
	v_cvt_pk_bf16_f32 v173, v176, v177
	global_store_dwordx4 v[132:133], v[170:173], off
	v_lshl_add_u64 v[130:131], v[130:131], 0, s[6:7]
	s_nop 0
	v_pk_mul_f32 v[170:171], v[150:151], v[46:47] op_sel_hi:[0,1]
	v_pk_mul_f32 v[172:173], v[150:151], v[48:49] op_sel_hi:[0,1]
	v_pk_mul_f32 v[174:175], v[150:151], v[42:43] op_sel_hi:[0,1]
	v_pk_mul_f32 v[176:177], v[150:151], v[44:45] op_sel_hi:[0,1]
	v_cvt_pk_bf16_f32 v170, v170, v171
	v_cvt_pk_bf16_f32 v171, v172, v173
	v_cvt_pk_bf16_f32 v172, v174, v175
	v_cvt_pk_bf16_f32 v173, v176, v177
	global_store_dwordx4 v[130:131], v[170:173], off
	v_lshl_add_u64 v[132:133], v[130:131], 0, s[80:81]
	s_nop 0
	v_pk_mul_f32 v[170:171], v[150:151], v[14:15] op_sel_hi:[0,1]
	v_pk_mul_f32 v[172:173], v[150:151], v[16:17] op_sel_hi:[0,1]
	v_pk_mul_f32 v[174:175], v[150:151], v[10:11] op_sel_hi:[0,1]
	v_pk_mul_f32 v[176:177], v[150:151], v[12:13] op_sel_hi:[0,1]
	v_cvt_pk_bf16_f32 v170, v170, v171
	v_cvt_pk_bf16_f32 v171, v172, v173
	v_cvt_pk_bf16_f32 v172, v174, v175
	v_cvt_pk_bf16_f32 v173, v176, v177
	global_store_dwordx4 v[132:133], v[170:173], off
	v_lshl_add_u64 v[130:131], v[130:131], 0, s[6:7]
	s_nop 0
	v_pk_mul_f32 v[170:171], v[150:151], v[38:39] op_sel_hi:[0,1]
	v_pk_mul_f32 v[172:173], v[150:151], v[40:41] op_sel_hi:[0,1]
	v_pk_mul_f32 v[174:175], v[150:151], v[34:35] op_sel_hi:[0,1]
	v_pk_mul_f32 v[176:177], v[150:151], v[36:37] op_sel_hi:[0,1]
	v_cvt_pk_bf16_f32 v170, v170, v171
	v_cvt_pk_bf16_f32 v171, v172, v173
	v_cvt_pk_bf16_f32 v172, v174, v175
	v_cvt_pk_bf16_f32 v173, v176, v177
	global_store_dwordx4 v[130:131], v[170:173], off
	v_lshl_add_u64 v[132:133], v[130:131], 0, s[80:81]
	s_nop 0
	v_pk_mul_f32 v[170:171], v[150:151], v[6:7] op_sel_hi:[0,1]
	v_pk_mul_f32 v[172:173], v[150:151], v[8:9] op_sel_hi:[0,1]
	v_pk_mul_f32 v[174:175], v[150:151], v[2:3] op_sel_hi:[0,1]
	v_pk_mul_f32 v[176:177], v[150:151], v[4:5] op_sel_hi:[0,1]
	v_cvt_pk_bf16_f32 v170, v170, v171
	v_cvt_pk_bf16_f32 v171, v172, v173
	v_cvt_pk_bf16_f32 v172, v174, v175
	v_cvt_pk_bf16_f32 v173, v176, v177
	global_store_dwordx4 v[132:133], v[170:173], off
	s_nop 0
.Lqk_done:
	s_nop 1
.LBB0_1112:
	s_mov_b64 s[0:1], 0
